# attention: softmax row sums accumulated on the VALU (f32 adds of the f32 exps, 4 partial sums per lane, one cross-half add per unit) instead of 4 extra ones-operand MFMAs per key tile
# baseline (speedup 1.0000x reference)
.LBB0_1420:
	s_nop 7
	v_add_f32_e32 v34, v34, v35
	v_add_f32_e32 v36, v36, v37
	s_nop 0
	v_add_f32_e32 v34, v34, v36
	s_nop 1
	ds_bpermute_b32 v35, v167, v34
	s_waitcnt lgkmcnt(0)
	v_add_f32_e32 v34, v34, v35
	v_div_scale_f32 v35, s[16:17], v34, v34, 1.0
	v_rcp_f32_e32 v36, v35
	v_div_scale_f32 v37, vcc, 1.0, v34, 1.0
	v_mov_b32_e32 v177, v151
	v_fma_f32 v38, -v35, v36, 1.0
	v_fmac_f32_e32 v36, v38, v36
	v_mul_f32_e32 v38, v37, v36
	v_fma_f32 v39, -v35, v38, v37
	v_fmac_f32_e32 v38, v39, v36
	v_fma_f32 v35, -v35, v38, v37
	v_div_fmas_f32 v35, v35, v36, v38
	v_div_fixup_f32 v36, v35, v34, 1.0
	v_lshlrev_b64 v[34:35], 10, v[170:171]
	v_lshl_add_u64 v[34:35], s[10:11], 0, v[34:35]
	v_mul_f32_e32 v18, v18, v36
	v_mul_f32_e32 v19, v19, v36
	v_lshl_add_u64 v[34:35], v[176:177], 1, v[34:35]
	v_mov_b32_e32 v169, v151
	v_cvt_pk_bf16_f32 v18, v18, v19
	v_mul_f32_e32 v19, v20, v36
	v_lshl_add_u64 v[34:35], v[34:35], 0, v[168:169]
	v_mul_f32_e32 v20, v21, v36
	v_cvt_pk_bf16_f32 v19, v19, v20
	global_store_dwordx2 v[34:35], v[18:19], off
	v_mul_f32_e32 v18, v22, v36
	v_mul_f32_e32 v19, v23, v36
	v_cvt_pk_bf16_f32 v18, v18, v19
	v_mul_f32_e32 v19, v24, v36
	v_mul_f32_e32 v20, v25, v36
	v_cvt_pk_bf16_f32 v19, v19, v20
	global_store_dwordx2 v[34:35], v[18:19], off offset:16
	v_mul_f32_e32 v18, v26, v36
	v_mul_f32_e32 v19, v27, v36
	v_cvt_pk_bf16_f32 v18, v18, v19
	v_mul_f32_e32 v19, v28, v36
	v_mul_f32_e32 v20, v29, v36
	v_cvt_pk_bf16_f32 v19, v19, v20
	global_store_dwordx2 v[34:35], v[18:19], off offset:32
	v_mul_f32_e32 v18, v30, v36
	v_mul_f32_e32 v19, v31, v36
	v_cvt_pk_bf16_f32 v18, v18, v19
	v_mul_f32_e32 v19, v32, v36
	v_mul_f32_e32 v2, v2, v36
	v_mul_f32_e32 v3, v3, v36
	v_mul_f32_e32 v20, v33, v36
	v_cvt_pk_bf16_f32 v19, v19, v20
	global_store_dwordx2 v[34:35], v[18:19], off offset:48
	v_cvt_pk_bf16_f32 v2, v2, v3
	v_mul_f32_e32 v3, v4, v36
	v_mul_f32_e32 v4, v5, v36
	v_cvt_pk_bf16_f32 v3, v3, v4
	global_store_dwordx2 v[34:35], v[2:3], off offset:64
	v_mul_f32_e32 v2, v6, v36
	v_mul_f32_e32 v3, v7, v36
	v_cvt_pk_bf16_f32 v2, v2, v3
	v_mul_f32_e32 v3, v8, v36
	v_mul_f32_e32 v4, v9, v36
	v_cvt_pk_bf16_f32 v3, v3, v4
	global_store_dwordx2 v[34:35], v[2:3], off offset:80
	v_mul_f32_e32 v2, v10, v36
	v_mul_f32_e32 v3, v11, v36
	v_cvt_pk_bf16_f32 v2, v2, v3
	v_mul_f32_e32 v3, v12, v36
	v_mul_f32_e32 v4, v13, v36
	v_cvt_pk_bf16_f32 v3, v3, v4
	global_store_dwordx2 v[34:35], v[2:3], off offset:96
	v_mul_f32_e32 v2, v14, v36
	v_mul_f32_e32 v3, v15, v36
	s_add_i32 s20, s20, s78
	v_cvt_pk_bf16_f32 v2, v2, v3
	v_mul_f32_e32 v3, v16, v36
	s_cmpk_gt_i32 s20, 0x2ff
	v_mul_f32_e32 v4, v17, v36
	v_cvt_pk_bf16_f32 v3, v3, v4
	global_store_dwordx2 v[34:35], v[2:3], off offset:112
	s_cbranch_scc1 .LBB0_1437

.LBB0_1435:
	s_add_i32 s12, s16, 2
	s_min_u32 s12, s12, s17
	v_lshlrev_b64 v[82:83], v160, s[12:13]
	s_mov_b32 s25, s16
	s_add_i32 s16, s16, 1
	v_lshl_add_u64 v[82:83], v[82:83], 1, v[172:173]
	s_min_u32 s26, s16, s17
	global_load_dwordx4 v[142:145], v[82:83], off
	v_mad_u64_u32 v[82:83], s[18:19], v178, s12, 0
	v_lshl_add_u64 v[82:83], v[82:83], 1, v[174:175]
	s_lshl_b32 s12, s26, 7
	global_load_dwordx4 v[146:149], v[82:83], off
	v_lshl_add_u64 v[82:83], v[180:181], 0, s[12:13]
	global_load_dwordx4 v[138:141], v[82:83], off
	s_and_b32 s12, s16, 1
	v_mov_b64_e32 v[112:113], v[64:65]
	s_mul_i32 s18, s12, 0x3400
	v_mov_b64_e32 v[110:111], v[62:63]
	v_mov_b64_e32 v[108:109], v[60:61]
	v_mov_b64_e32 v[106:107], v[58:59]
	v_mov_b64_e32 v[104:105], v[56:57]
	v_mov_b64_e32 v[102:103], v[54:55]
	v_mov_b64_e32 v[100:101], v[52:53]
	v_mov_b64_e32 v[98:99], v[50:51]
	v_add_u32_e32 v50, s18, v189
	ds_read_b128 v[194:197], v50
	ds_read_b128 v[198:201], v50 offset:32
	ds_read_b128 v[204:207], v50 offset:64
	ds_read_b128 v[208:211], v50 offset:96
	ds_read_b128 v[212:215], v50 offset:128
	ds_read_b128 v[216:219], v50 offset:160
	ds_read_b128 v[220:223], v50 offset:6656
	ds_read_b128 v[224:227], v50 offset:6688
	ds_read_b128 v[228:231], v50 offset:6720
	ds_read_b128 v[232:235], v50 offset:6752
	ds_read_b128 v[236:239], v50 offset:6784
	ds_read_b128 v[240:243], v50 offset:6816
	v_xor_b32_e32 v82, 0x80000000, v169
	v_mov_b32_e32 v83, v82
	v_mov_b32_e32 v84, v82
	v_mov_b32_e32 v85, v82
	v_mov_b32_e32 v86, v82
	v_mov_b32_e32 v87, v82
	v_mov_b32_e32 v88, v82
	v_mov_b32_e32 v89, v82
	v_mov_b32_e32 v90, v82
	v_mov_b32_e32 v91, v82
	v_mov_b32_e32 v92, v82
	v_mov_b32_e32 v93, v82
	v_mov_b32_e32 v94, v82
	v_mov_b32_e32 v95, v82
	v_mov_b32_e32 v96, v82
	v_mov_b32_e32 v97, v82
	s_waitcnt lgkmcnt(11)
	s_nop 0
	v_mfma_f32_32x32x16_bf16 v[50:65], v[194:197], v[114:117], v[82:97]
	v_exp_f32_e32 v177, v98
	v_exp_f32_e32 v179, v99
	v_exp_f32_e32 v203, v100
	v_exp_f32_e32 v244, v101
	v_exp_f32_e32 v245, v102
	v_exp_f32_e32 v246, v103
	v_exp_f32_e32 v247, v104
	s_waitcnt lgkmcnt(10)
	v_mfma_f32_32x32x16_bf16 v[50:65], v[198:201], v[118:121], v[50:65]
	v_exp_f32_e32 v248, v105
	v_exp_f32_e32 v249, v110
	v_exp_f32_e32 v250, v111
	v_exp_f32_e32 v251, v112
	v_exp_f32_e32 v252, v113
	s_waitcnt lgkmcnt(9)
	v_mfma_f32_32x32x16_bf16 v[50:65], v[204:207], v[122:125], v[50:65]
	s_waitcnt lgkmcnt(8)
	v_mfma_f32_32x32x16_bf16 v[50:65], v[208:211], v[126:129], v[50:65]
	s_waitcnt lgkmcnt(7)
	v_mfma_f32_32x32x16_bf16 v[50:65], v[212:215], v[130:133], v[50:65]
	v_exp_f32_e32 v212, v106
	v_exp_f32_e32 v213, v107
	v_exp_f32_e32 v214, v108
	v_exp_f32_e32 v215, v109
	s_waitcnt lgkmcnt(6)
	v_mfma_f32_32x32x16_bf16 v[50:65], v[216:219], v[134:137], v[50:65]
	s_and_b32 s18, s25, 1
	s_mul_i32 s19, s18, 0x2200
	v_add_u32_e32 v194, s19, v190
	v_add_u32_e32 v110, 0x6800, v194
	v_add_u32_e32 v208, 0x7800, v194
	ds_read2_b64 v[98:101], v110 offset1:2
	ds_read2_b64 v[102:105], v110 offset0:4 offset1:6
	ds_read2_b64 v[106:109], v110 offset0:8 offset1:10
	ds_read2_b64 v[110:113], v110 offset0:12 offset1:14
	ds_read2_b64 v[194:197], v208 offset0:32 offset1:34
	ds_read2_b64 v[198:201], v208 offset0:36 offset1:38
	ds_read2_b64 v[204:207], v208 offset0:40 offset1:42
	ds_read2_b64 v[208:211], v208 offset0:44 offset1:46
	s_waitcnt lgkmcnt(13)
	v_mfma_f32_32x32x16_bf16 v[82:97], v[220:223], v[114:117], v[82:97]
	v_exp_f32_e32 v74, v74
	v_exp_f32_e32 v75, v75
	v_exp_f32_e32 v76, v76
	v_exp_f32_e32 v77, v77
	v_exp_f32_e32 v78, v78
	v_exp_f32_e32 v79, v79
	v_exp_f32_e32 v80, v80
	s_waitcnt lgkmcnt(12)
	v_mfma_f32_32x32x16_bf16 v[82:97], v[224:227], v[118:121], v[82:97]
	v_exp_f32_e32 v81, v81
	v_exp_f32_e32 v216, v66
	v_exp_f32_e32 v217, v67
	v_exp_f32_e32 v218, v68
	v_exp_f32_e32 v219, v69
	v_exp_f32_e32 v220, v70
	v_exp_f32_e32 v221, v71
	s_waitcnt lgkmcnt(11)
	v_mfma_f32_32x32x16_bf16 v[82:97], v[228:231], v[122:125], v[82:97]
	v_exp_f32_e32 v222, v72
	v_exp_f32_e32 v223, v73
	v_cvt_pk_bf16_f32 v66, v177, v179
	v_add_f32_e32 v34, v34, v177
	v_add_f32_e32 v35, v35, v179
	v_cvt_pk_bf16_f32 v67, v203, v244
	v_add_f32_e32 v36, v36, v203
	v_add_f32_e32 v37, v37, v244
	v_cvt_pk_bf16_f32 v68, v245, v246
	v_add_f32_e32 v34, v34, v245
	v_add_f32_e32 v35, v35, v246
	v_cvt_pk_bf16_f32 v69, v247, v248
	v_add_f32_e32 v36, v36, v247
	v_add_f32_e32 v37, v37, v248
	v_cvt_pk_bf16_f32 v70, v212, v213
	v_add_f32_e32 v34, v34, v212
	v_add_f32_e32 v35, v35, v213
	s_waitcnt lgkmcnt(10)
	v_mfma_f32_32x32x16_bf16 v[82:97], v[232:235], v[126:129], v[82:97]
	v_cvt_pk_bf16_f32 v71, v214, v215
	v_add_f32_e32 v36, v36, v214
	v_add_f32_e32 v37, v37, v215
	v_cvt_pk_bf16_f32 v72, v249, v250
	v_add_f32_e32 v34, v34, v249
	v_add_f32_e32 v35, v35, v250
	v_cvt_pk_bf16_f32 v73, v251, v252
	v_add_f32_e32 v36, v36, v251
	v_add_f32_e32 v37, v37, v252
	v_cvt_pk_bf16_f32 v212, v216, v217
	v_add_f32_e32 v34, v34, v216
	v_add_f32_e32 v35, v35, v217
	v_cvt_pk_bf16_f32 v213, v218, v219
	v_add_f32_e32 v36, v36, v218
	v_add_f32_e32 v37, v37, v219
	v_cvt_pk_bf16_f32 v214, v220, v221
	v_add_f32_e32 v34, v34, v220
	v_add_f32_e32 v35, v35, v221
	v_cvt_pk_bf16_f32 v215, v222, v223
	v_add_f32_e32 v36, v36, v222
	v_add_f32_e32 v37, v37, v223
	s_waitcnt lgkmcnt(9)
	v_mfma_f32_32x32x16_bf16 v[82:97], v[236:239], v[130:133], v[82:97]
	v_cvt_pk_bf16_f32 v216, v74, v75
	v_add_f32_e32 v34, v34, v74
	v_add_f32_e32 v35, v35, v75
	v_cvt_pk_bf16_f32 v217, v76, v77
	v_add_f32_e32 v36, v36, v76
	v_add_f32_e32 v37, v37, v77
	v_cvt_pk_bf16_f32 v218, v78, v79
	v_add_f32_e32 v34, v34, v78
	v_add_f32_e32 v35, v35, v79
	v_cvt_pk_bf16_f32 v219, v80, v81
	v_add_f32_e32 v36, v36, v80
	v_add_f32_e32 v37, v37, v81
	s_waitcnt lgkmcnt(7)
	v_mfma_f32_32x32x16_bf16 v[18:33], v[98:101], v[66:69], v[18:33]
	s_nop 0
	s_nop 0
	s_mulk_i32 s18, 0x3400
	s_add_i32 s18, s18, 0
	s_mulk_i32 s12, 0x2200
	s_waitcnt lgkmcnt(3)
	v_mfma_f32_32x32x16_bf16 v[2:17], v[194:197], v[66:69], v[2:17]
	s_nop 0
	v_mfma_f32_32x32x16_bf16 v[18:33], v[102:105], v[70:73], v[18:33]
	s_waitcnt lgkmcnt(2)
	v_mfma_f32_32x32x16_bf16 v[2:17], v[198:201], v[70:73], v[2:17]
	s_nop 0
	v_mov_b64_e32 v[66:67], v[82:83]
	v_mov_b64_e32 v[68:69], v[84:85]
	v_mov_b64_e32 v[70:71], v[86:87]
	v_mov_b64_e32 v[72:73], v[88:89]
	v_mov_b64_e32 v[74:75], v[90:91]
	v_mov_b64_e32 v[76:77], v[92:93]
	v_mov_b64_e32 v[78:79], v[94:95]
	v_mov_b64_e32 v[80:81], v[96:97]
	v_add3_u32 v82, s18, v184, v185
	s_waitcnt vmcnt(2)
	ds_write_b128 v82, v[142:145]
	v_add3_u32 v82, s18, v186, v187
	v_mfma_f32_32x32x16_bf16 v[66:81], v[240:243], v[134:137], v[66:81]
	s_waitcnt vmcnt(1)
	ds_write_b128 v82, v[146:149]
	v_max3_f32 v82, v50, v66, v51
	v_add_u32_e32 v84, s12, v188
	v_max3_f32 v82, v82, v67, v52
	v_add_u32_e32 v84, 0x6800, v84
	v_max3_f32 v82, v82, v68, v53
	s_waitcnt vmcnt(0)
	ds_write2_b64 v84, v[138:139], v[140:141] offset1:1
	v_max3_f32 v82, v82, v69, v54
	v_mfma_f32_32x32x16_bf16 v[18:33], v[106:109], v[212:215], v[18:33]
	v_max3_f32 v82, v82, v70, v55
	s_nop 4
	v_max_f32_e32 v83, v81, v81
	v_max3_f32 v82, v82, v71, v56
	s_nop 0
	v_max3_f32 v82, v82, v72, v57
	s_nop 0
	v_max3_f32 v82, v82, v73, v58
	s_waitcnt lgkmcnt(4)
	v_mfma_f32_32x32x16_bf16 v[2:17], v[204:207], v[212:215], v[2:17]
	v_max3_f32 v82, v82, v74, v59
	s_nop 0
	v_max3_f32 v82, v82, v75, v60
	s_nop 0
	v_max3_f32 v82, v82, v76, v61
	s_nop 0
	v_max3_f32 v82, v82, v77, v62
	s_nop 0
	v_max3_f32 v82, v82, v78, v63
	s_nop 0
	v_max3_f32 v82, v82, v79, v64
	s_nop 0
	v_max3_f32 v82, v82, v80, v65
	s_nop 0
	v_max_f32_e32 v82, v82, v82
	v_max_f32_e32 v82, v82, v83
	v_mfma_f32_32x32x16_bf16 v[18:33], v[110:113], v[216:219], v[18:33]
	ds_bpermute_b32 v83, v167, v82
	s_waitcnt lgkmcnt(0)
	v_max_f32_e32 v83, v83, v83
	v_max_f32_e32 v82, v82, v83
	v_mfma_f32_32x32x16_bf16 v[2:17], v[208:211], v[216:219], v[2:17]
	v_cmp_lt_f32_e32 vcc, s23, v82
	s_nop 0
	s_cbranch_vccz .LBB0_1434
	v_max_f32_e32 v82, v82, v82
	v_max_f32_e32 v83, 0, v82
	v_exp_f32_e64 v82, -v83
	v_sub_f32_e32 v65, v65, v83
	v_sub_f32_e32 v64, v64, v83
	v_sub_f32_e32 v63, v63, v83
	v_sub_f32_e32 v62, v62, v83
	v_sub_f32_e32 v61, v61, v83
	v_sub_f32_e32 v60, v60, v83
	v_sub_f32_e32 v59, v59, v83
	v_sub_f32_e32 v58, v58, v83
	v_sub_f32_e32 v57, v57, v83
	v_sub_f32_e32 v56, v56, v83
	v_sub_f32_e32 v55, v55, v83
	v_sub_f32_e32 v54, v54, v83
	v_sub_f32_e32 v53, v53, v83
	v_sub_f32_e32 v52, v52, v83
	v_sub_f32_e32 v51, v51, v83
	v_sub_f32_e32 v50, v50, v83
	v_sub_f32_e32 v81, v81, v83
	v_sub_f32_e32 v80, v80, v83
	v_sub_f32_e32 v79, v79, v83
	v_sub_f32_e32 v78, v78, v83
	v_sub_f32_e32 v77, v77, v83
	v_sub_f32_e32 v76, v76, v83
	v_sub_f32_e32 v75, v75, v83
	v_sub_f32_e32 v74, v74, v83
	v_sub_f32_e32 v73, v73, v83
	v_sub_f32_e32 v72, v72, v83
	v_sub_f32_e32 v71, v71, v83
	v_sub_f32_e32 v70, v70, v83
	v_sub_f32_e32 v69, v69, v83
	v_sub_f32_e32 v68, v68, v83
	v_sub_f32_e32 v67, v67, v83
	v_sub_f32_e32 v66, v66, v83
	v_pk_mul_f32 v[32:33], v[32:33], v[82:83] op_sel_hi:[1,0]
	v_pk_mul_f32 v[30:31], v[30:31], v[82:83] op_sel_hi:[1,0]
	v_pk_mul_f32 v[28:29], v[28:29], v[82:83] op_sel_hi:[1,0]
	v_pk_mul_f32 v[26:27], v[26:27], v[82:83] op_sel_hi:[1,0]
	v_pk_mul_f32 v[24:25], v[24:25], v[82:83] op_sel_hi:[1,0]
	v_pk_mul_f32 v[22:23], v[22:23], v[82:83] op_sel_hi:[1,0]
	v_pk_mul_f32 v[20:21], v[20:21], v[82:83] op_sel_hi:[1,0]
	v_pk_mul_f32 v[18:19], v[18:19], v[82:83] op_sel_hi:[1,0]
	v_pk_mul_f32 v[16:17], v[16:17], v[82:83] op_sel_hi:[1,0]
	v_pk_mul_f32 v[14:15], v[14:15], v[82:83] op_sel_hi:[1,0]
	v_pk_mul_f32 v[12:13], v[12:13], v[82:83] op_sel_hi:[1,0]
	v_pk_mul_f32 v[10:11], v[10:11], v[82:83] op_sel_hi:[1,0]
	v_pk_mul_f32 v[8:9], v[8:9], v[82:83] op_sel_hi:[1,0]
	v_pk_mul_f32 v[6:7], v[6:7], v[82:83] op_sel_hi:[1,0]
	v_pk_mul_f32 v[4:5], v[4:5], v[82:83] op_sel_hi:[1,0]
	v_pk_mul_f32 v[2:3], v[2:3], v[82:83] op_sel_hi:[1,0]
	v_pk_mul_f32 v[36:37], v[36:37], v[82:83] op_sel_hi:[1,0]
	v_pk_mul_f32 v[34:35], v[34:35], v[82:83] op_sel_hi:[1,0]
	v_add_f32_e32 v169, v169, v83
	s_branch .LBB0_1434
